# v092 + row sum-of-squares (ss2) fetched before the activation loads in ab_rows so its latency is hidden
# baseline (speedup 1.0000x reference)
.LBB0_165:
	v_ashrrev_i32_e32 v15, 31, v14
	v_lshlrev_b64 v[2:3], 11, v[14:15]
	v_lshl_add_u64 v[16:17], v[12:13], 0, v[2:3]
	v_lshl_or_b32 v152, v19, 4, v20
	v_ashrrev_i32_e32 v153, 31, v152
	v_lshl_add_u64 v[154:155], v[152:153], 2, s[4:5]
	global_load_dwordx4 v[156:159], v[154:155], off
	global_load_dwordx4 v[22:25], v[16:17], off
	global_load_dwordx4 v[26:29], v[16:17], off offset:64
	global_load_dwordx4 v[30:33], v[16:17], off offset:128
	global_load_dwordx4 v[34:37], v[16:17], off offset:192
	global_load_dwordx4 v[38:41], v[16:17], off offset:256
	global_load_dwordx4 v[42:45], v[16:17], off offset:320
	global_load_dwordx4 v[46:49], v[16:17], off offset:384
	global_load_dwordx4 v[50:53], v[16:17], off offset:448
	global_load_dwordx4 v[54:57], v[16:17], off offset:512
	global_load_dwordx4 v[58:61], v[16:17], off offset:576
	global_load_dwordx4 v[62:65], v[16:17], off offset:640
	global_load_dwordx4 v[66:69], v[16:17], off offset:704
	global_load_dwordx4 v[70:73], v[16:17], off offset:768
	global_load_dwordx4 v[74:77], v[16:17], off offset:832
	global_load_dwordx4 v[78:81], v[16:17], off offset:896
	global_load_dwordx4 v[82:85], v[16:17], off offset:960
	global_load_dwordx4 v[86:89], v[16:17], off offset:1024
	global_load_dwordx4 v[90:93], v[16:17], off offset:1088
	global_load_dwordx4 v[94:97], v[16:17], off offset:1152
	global_load_dwordx4 v[98:101], v[16:17], off offset:1216
	global_load_dwordx4 v[102:105], v[16:17], off offset:1280
	global_load_dwordx4 v[106:109], v[16:17], off offset:1344
	global_load_dwordx4 v[110:113], v[16:17], off offset:1408
	global_load_dwordx4 v[114:117], v[16:17], off offset:1472
	global_load_dwordx4 v[118:121], v[16:17], off offset:1536
	global_load_dwordx4 v[122:125], v[16:17], off offset:1600
	global_load_dwordx4 v[126:129], v[16:17], off offset:1664
	global_load_dwordx4 v[130:133], v[16:17], off offset:1728
	global_load_dwordx4 v[134:137], v[16:17], off offset:1792
	global_load_dwordx4 v[138:141], v[16:17], off offset:1856
	global_load_dwordx4 v[142:145], v[16:17], off offset:1920
	global_load_dwordx4 v[146:149], v[16:17], off offset:1984
	v_mul_u32_u24_e32 v150, 0x810, v18
	v_lshl_add_u32 v150, v20, 2, v150
	v_mov_b32_e32 v2, 0
	v_mov_b32_e32 v3, 0
	v_mov_b32_e32 v4, 0
	v_mov_b32_e32 v5, 0
	ds_read_b128 v[160:163], v150
	ds_read_b128 v[164:167], v150 offset:64
	ds_read_b128 v[168:171], v150 offset:128
	ds_read_b128 v[172:175], v150 offset:192
	s_waitcnt vmcnt(31) lgkmcnt(3)
	v_mfma_f32_16x16x32_bf16 v[2:5], v[22:25], v[160:163], v[2:5]
	ds_read_b128 v[176:179], v150 offset:256
	s_waitcnt vmcnt(30) lgkmcnt(3)
	v_mfma_f32_16x16x32_bf16 v[2:5], v[26:29], v[164:167], v[2:5]
	ds_read_b128 v[180:183], v150 offset:320
	s_waitcnt vmcnt(29) lgkmcnt(3)
	v_mfma_f32_16x16x32_bf16 v[2:5], v[30:33], v[168:171], v[2:5]
	ds_read_b128 v[184:187], v150 offset:384
	s_waitcnt vmcnt(28) lgkmcnt(3)
	v_mfma_f32_16x16x32_bf16 v[2:5], v[34:37], v[172:175], v[2:5]
	ds_read_b128 v[188:191], v150 offset:448
	s_waitcnt vmcnt(27) lgkmcnt(3)
	v_mfma_f32_16x16x32_bf16 v[2:5], v[38:41], v[176:179], v[2:5]
	ds_read_b128 v[160:163], v150 offset:512
	s_waitcnt vmcnt(26) lgkmcnt(3)
	v_mfma_f32_16x16x32_bf16 v[2:5], v[42:45], v[180:183], v[2:5]
	ds_read_b128 v[164:167], v150 offset:576
	s_waitcnt vmcnt(25) lgkmcnt(3)
	v_mfma_f32_16x16x32_bf16 v[2:5], v[46:49], v[184:187], v[2:5]
	ds_read_b128 v[168:171], v150 offset:640
	s_waitcnt vmcnt(24) lgkmcnt(3)
	v_mfma_f32_16x16x32_bf16 v[2:5], v[50:53], v[188:191], v[2:5]
	ds_read_b128 v[172:175], v150 offset:704
	s_waitcnt vmcnt(23) lgkmcnt(3)
	v_mfma_f32_16x16x32_bf16 v[2:5], v[54:57], v[160:163], v[2:5]
	ds_read_b128 v[176:179], v150 offset:768
	s_waitcnt vmcnt(22) lgkmcnt(3)
	v_mfma_f32_16x16x32_bf16 v[2:5], v[58:61], v[164:167], v[2:5]
	ds_read_b128 v[180:183], v150 offset:832
	s_waitcnt vmcnt(21) lgkmcnt(3)
	v_mfma_f32_16x16x32_bf16 v[2:5], v[62:65], v[168:171], v[2:5]
	ds_read_b128 v[184:187], v150 offset:896
	s_waitcnt vmcnt(20) lgkmcnt(3)
	v_mfma_f32_16x16x32_bf16 v[2:5], v[66:69], v[172:175], v[2:5]
	ds_read_b128 v[188:191], v150 offset:960
	s_waitcnt vmcnt(19) lgkmcnt(3)
	v_mfma_f32_16x16x32_bf16 v[2:5], v[70:73], v[176:179], v[2:5]
	ds_read_b128 v[160:163], v150 offset:1024
	s_waitcnt vmcnt(18) lgkmcnt(3)
	v_mfma_f32_16x16x32_bf16 v[2:5], v[74:77], v[180:183], v[2:5]
	ds_read_b128 v[164:167], v150 offset:1088
	s_waitcnt vmcnt(17) lgkmcnt(3)
	v_mfma_f32_16x16x32_bf16 v[2:5], v[78:81], v[184:187], v[2:5]
	ds_read_b128 v[168:171], v150 offset:1152
	s_waitcnt vmcnt(16) lgkmcnt(3)
	v_mfma_f32_16x16x32_bf16 v[2:5], v[82:85], v[188:191], v[2:5]
	ds_read_b128 v[172:175], v150 offset:1216
	s_waitcnt vmcnt(15) lgkmcnt(3)
	v_mfma_f32_16x16x32_bf16 v[2:5], v[86:89], v[160:163], v[2:5]
	ds_read_b128 v[176:179], v150 offset:1280
	s_waitcnt vmcnt(14) lgkmcnt(3)
	v_mfma_f32_16x16x32_bf16 v[2:5], v[90:93], v[164:167], v[2:5]
	ds_read_b128 v[180:183], v150 offset:1344
	s_waitcnt vmcnt(13) lgkmcnt(3)
	v_mfma_f32_16x16x32_bf16 v[2:5], v[94:97], v[168:171], v[2:5]
	ds_read_b128 v[184:187], v150 offset:1408
	s_waitcnt vmcnt(12) lgkmcnt(3)
	v_mfma_f32_16x16x32_bf16 v[2:5], v[98:101], v[172:175], v[2:5]
	ds_read_b128 v[188:191], v150 offset:1472
	s_waitcnt vmcnt(11) lgkmcnt(3)
	v_mfma_f32_16x16x32_bf16 v[2:5], v[102:105], v[176:179], v[2:5]
	ds_read_b128 v[160:163], v150 offset:1536
	s_waitcnt vmcnt(10) lgkmcnt(3)
	v_mfma_f32_16x16x32_bf16 v[2:5], v[106:109], v[180:183], v[2:5]
	ds_read_b128 v[164:167], v150 offset:1600
	s_waitcnt vmcnt(9) lgkmcnt(3)
	v_mfma_f32_16x16x32_bf16 v[2:5], v[110:113], v[184:187], v[2:5]
	ds_read_b128 v[168:171], v150 offset:1664
	s_waitcnt vmcnt(8) lgkmcnt(3)
	v_mfma_f32_16x16x32_bf16 v[2:5], v[114:117], v[188:191], v[2:5]
	ds_read_b128 v[172:175], v150 offset:1728
	s_waitcnt vmcnt(7) lgkmcnt(3)
	v_mfma_f32_16x16x32_bf16 v[2:5], v[118:121], v[160:163], v[2:5]
	ds_read_b128 v[176:179], v150 offset:1792
	s_waitcnt vmcnt(6) lgkmcnt(3)
	v_mfma_f32_16x16x32_bf16 v[2:5], v[122:125], v[164:167], v[2:5]
	ds_read_b128 v[180:183], v150 offset:1856
	s_waitcnt vmcnt(5) lgkmcnt(3)
	v_mfma_f32_16x16x32_bf16 v[2:5], v[126:129], v[168:171], v[2:5]
	ds_read_b128 v[184:187], v150 offset:1920
	s_waitcnt vmcnt(4) lgkmcnt(3)
	v_mfma_f32_16x16x32_bf16 v[2:5], v[130:133], v[172:175], v[2:5]
	ds_read_b128 v[188:191], v150 offset:1984
	s_waitcnt vmcnt(3) lgkmcnt(3)
	v_mfma_f32_16x16x32_bf16 v[2:5], v[134:137], v[176:179], v[2:5]
	s_waitcnt vmcnt(2) lgkmcnt(2)
	v_mfma_f32_16x16x32_bf16 v[2:5], v[138:141], v[180:183], v[2:5]
	s_waitcnt vmcnt(1) lgkmcnt(1)
	v_mfma_f32_16x16x32_bf16 v[2:5], v[142:145], v[184:187], v[2:5]
	s_waitcnt vmcnt(0) lgkmcnt(0)
	v_mfma_f32_16x16x32_bf16 v[2:5], v[146:149], v[188:191], v[2:5]
	v_lshlrev_b64 v[192:193], 5, v[152:153]
	v_lshl_add_u64 v[192:193], v[8:9], 0, v[192:193]
	s_nop 7
	s_nop 1
	s_and_saveexec_b64 s[12:13], s[2:3]
	s_cbranch_execz .LBB0_164
	s_waitcnt vmcnt(0)
	v_fmamk_f32 v15, v156, 0x3a800000, v21
	v_mul_f32_e32 v17, 0x4b800000, v15
	v_cmp_gt_f32_e32 vcc, s14, v15
	s_nop 1
	v_cndmask_b32_e32 v15, v15, v17, vcc
	v_rsq_f32_e32 v15, v15
	s_nop 0
	v_mul_f32_e32 v17, 0x45800000, v15
	v_cndmask_b32_e32 v15, v15, v17, vcc
	v_mul_f32_e32 v2, v2, v15
	global_store_dword v[192:193], v2, off
	v_fmamk_f32 v15, v157, 0x3a800000, v21
	v_mul_f32_e32 v17, 0x4b800000, v15
	v_cmp_gt_f32_e32 vcc, s14, v15
	s_nop 1
	v_cndmask_b32_e32 v15, v15, v17, vcc
	v_rsq_f32_e32 v15, v15
	s_nop 0
	v_mul_f32_e32 v17, 0x45800000, v15
	v_cndmask_b32_e32 v15, v15, v17, vcc
	v_mul_f32_e32 v3, v3, v15
	global_store_dword v[192:193], v3, off offset:32
	v_fmamk_f32 v15, v158, 0x3a800000, v21
	v_mul_f32_e32 v17, 0x4b800000, v15
	v_cmp_gt_f32_e32 vcc, s14, v15
	s_nop 1
	v_cndmask_b32_e32 v15, v15, v17, vcc
	v_rsq_f32_e32 v15, v15
	s_nop 0
	v_mul_f32_e32 v17, 0x45800000, v15
	v_cndmask_b32_e32 v15, v15, v17, vcc
	v_mul_f32_e32 v4, v4, v15
	global_store_dword v[192:193], v4, off offset:64
	v_fmamk_f32 v15, v159, 0x3a800000, v21
	v_mul_f32_e32 v17, 0x4b800000, v15
	v_cmp_gt_f32_e32 vcc, s14, v15
	s_nop 1
	v_cndmask_b32_e32 v15, v15, v17, vcc
	v_rsq_f32_e32 v15, v15
	s_nop 0
	v_mul_f32_e32 v17, 0x45800000, v15
	v_cndmask_b32_e32 v15, v15, v17, vcc
	v_mul_f32_e32 v5, v5, v15
	global_store_dword v[192:193], v5, off offset:96
	s_branch .LBB0_164
